# v93 minus the L2 touch block, plus attention unit order 31-s, s, 16+s, 15-s (a head's 8 workgroups start their two long double-units step-aligned and share K/V tiles in L2)
# baseline (speedup 1.0000x reference)
.LBB0_637:
	s_cmp_lt_u32 s75, 8
	s_cbranch_scc0 .LBB0_641
	s_cmp_lt_u32 s75, 2
	s_mov_b32 s2, s66
	s_cbranch_scc1 .LBB0_640
	s_cmp_eq_u32 s8, 2
	s_cselect_b32 s0, s63, s67
	s_cmp_eq_u32 s8, 1
	s_cselect_b32 s2, s61, s0

.LBB0_686:
	s_add_i32 s0, s2, 0x2000
	s_cmpk_lg_i32 s2, 0x4000
	v_add_f32_e32 v64, v64, v65
	s_cselect_b32 s0, s0, 0
	s_add_i32 s1, s25, -1
	v_add_f32_e32 v64, v64, v136
	v_lshl_add_u64 v[228:229], v[228:229], 0, s[12:13]
	v_lshl_add_u64 v[226:227], v[226:227], 0, s[12:13]
	s_cmp_lt_i32 s1, s26
	v_lshl_add_u64 v[224:225], v[224:225], 0, s[12:13]
	s_cbranch_scc0 .LBB0_688
	s_mov_b32 s77, s25
	s_mov_b32 s25, s24
	s_mov_b32 s24, s0
	s_branch .LBB0_652
.LBB0_688:
	s_bitcmp1_b32 s85, 8
	s_cbranch_scc1 .Lmy_fs_go
	v_mov_b32_e32 v65, v64
	s_nop 1
	v_permlane32_swap_b32_e32 v64, v65
	v_cmp_gt_u32_e32 vcc, 32, v242
	s_branch .Lmy_fs_join
